# same as the early-invalidate seam version, seam poll bound raised to 131072 polls (robustness)
# speedup vs baseline: 1.0019x; 1.0019x over previous
.Lsm0_poll:
	s_waitcnt lgkmcnt(0)
	v_add_u32_e32 v6, 1, v3
	v_mul_lo_u32 v6, v6, v2
	s_add_u32 s98, s40, 0x1e03400
	s_addc_u32 s99, s41, 0
	v_mov_b32_e32 v7, 0
	s_mov_b32 s101, 0x20000

.Lsm6_poll:
	s_waitcnt lgkmcnt(0)
	v_readlane_b32 s98, v253, 43
	v_readlane_b32 s99, v253, 44
	v_add_u32_e32 v4, 1, v1
	v_mul_lo_u32 v4, v4, v0
	s_mov_b32 s101, 0x20000
	s_nop 4
